# v20: v15 + leading half's alignment barrier moved behind the issue of its first epilogue loads in FF2 and the output projection (its load latency overlaps the trailing half's last MFMA block)
# baseline (speedup 1.0000x reference)
.LBB0_1496:
	v_mov_b32_e32 v156, v223
	s_lshl_b32 s27, s22, 8
	v_ashrrev_i32_e32 v128, 1, v156
	s_or_b32 s27, s27, s52
	v_and_b32_e32 v128, -8, v128
	v_add_u32_e32 v192, s27, v128
	v_ashrrev_i32_e32 v193, 31, v192
	v_lshlrev_b64 v[152:153], 2, v[192:193]
	v_lshl_add_u64 v[140:141], s[18:19], 0, v[152:153]
	v_lshl_add_u64 v[154:155], s[14:15], 0, v[152:153]
	global_load_dwordx4 v[128:131], v[140:141], off offset:16
	global_load_dwordx4 v[132:135], v[140:141], off
	global_load_dwordx4 v[136:139], v[140:141], off offset:528
	s_nop 0
	global_load_dwordx4 v[140:143], v[140:141], off offset:512
	s_nop 0
	global_load_dwordx4 v[144:147], v[154:155], off offset:16
	global_load_dwordx4 v[148:151], v[154:155], off
	s_lshl_b32 s0, s36, 8
	s_add_i32 s0, s0, s51
	v_and_or_b32 v214, v156, 15, s0
	v_ashrrev_i32_e32 v215, 31, v214
	v_lshl_add_u64 v[212:213], s[6:7], 0, v[152:153]
	v_or_b32_e32 v220, 16, v214
	v_ashrrev_i32_e32 v221, 31, v220
	v_or_b32_e32 v218, 32, v214
	v_ashrrev_i32_e32 v219, 31, v218
	v_or_b32_e32 v216, 48, v214
	v_ashrrev_i32_e32 v217, 31, v216
	v_cmp_gt_u32_e32 vcc, 16, v156
	v_lshl_add_u64 v[210:211], v[214:215], 2, s[12:13]
	v_cvt_f32_i32_e32 v127, v127
	v_cvt_f32_i32_e32 v126, v126
	v_cvt_f32_i32_e32 v125, v125
	v_cvt_f32_i32_e32 v124, v124
	v_cvt_f32_i32_e32 v123, v123
	v_cvt_f32_i32_e32 v122, v122
	v_cvt_f32_i32_e32 v121, v121
	v_cvt_f32_i32_e32 v120, v120
	v_cvt_f32_i32_e32 v119, v119
	v_cvt_f32_i32_e32 v118, v118
	v_cvt_f32_i32_e32 v117, v117
	v_cvt_f32_i32_e32 v116, v116
	v_cvt_f32_i32_e32 v115, v115
	v_cvt_f32_i32_e32 v114, v114
	v_cvt_f32_i32_e32 v113, v113
	v_cvt_f32_i32_e32 v112, v112
	v_lshlrev_b64 v[238:239], 13, v[214:215]
	s_lshl_b32 s36, s22, 2
	s_ashr_i32 s37, s36, 31
	s_cmp_lg_u64 s[20:21], 0
	s_cbranch_scc0 .Lhs_p6
	s_barrier
.Lhs_p6:
	s_waitcnt vmcnt(1)
	v_pk_mul_f32 v[130:131], v[130:131], v[146:147]
	s_waitcnt vmcnt(0)
	v_pk_mul_f32 v[134:135], v[134:135], v[150:151]
	v_pk_mul_f32 v[132:133], v[132:133], v[148:149]
	v_pk_mul_f32 v[128:129], v[128:129], v[144:145]
	v_pk_mul_f32 v[194:195], v[134:135], s[24:25] op_sel_hi:[1,0]
	v_pk_mul_f32 v[196:197], v[132:133], s[24:25] op_sel_hi:[1,0]
	v_pk_mul_f32 v[198:199], v[130:131], s[24:25] op_sel_hi:[1,0]
	v_pk_mul_f32 v[200:201], v[128:129], s[24:25] op_sel_hi:[1,0]
	global_load_dwordx4 v[128:131], v[154:155], off offset:528
	global_load_dwordx4 v[132:135], v[154:155], off offset:512
	s_waitcnt vmcnt(1)
	v_pk_mul_f32 v[128:129], v[136:137], v[128:129]
	s_nop 0
	v_pk_mul_f32 v[202:203], v[128:129], s[24:25] op_sel_hi:[1,0]
	v_lshlrev_b64 v[128:129], 14, v[214:215]
	v_lshl_add_u64 v[128:129], v[212:213], 0, v[128:129]
	global_load_dwordx4 v[184:187], v[128:129], off offset:16
	global_load_dwordx4 v[234:237], v[128:129], off
	global_load_dwordx4 v[176:179], v[128:129], off offset:528
	global_load_dwordx4 v[180:183], v[128:129], off offset:512
	v_lshlrev_b64 v[128:129], 14, v[220:221]
	v_lshl_add_u64 v[128:129], v[212:213], 0, v[128:129]
	global_load_dwordx4 v[164:167], v[128:129], off offset:16
	global_load_dwordx4 v[172:175], v[128:129], off
	global_load_dwordx4 v[160:163], v[128:129], off offset:528
	global_load_dwordx4 v[168:171], v[128:129], off offset:512
	v_lshlrev_b64 v[128:129], 14, v[218:219]
	v_lshl_add_u64 v[128:129], v[212:213], 0, v[128:129]
	global_load_dwordx4 v[148:151], v[128:129], off offset:16
	global_load_dwordx4 v[156:159], v[128:129], off
	global_load_dwordx4 v[144:147], v[128:129], off offset:528
	global_load_dwordx4 v[152:155], v[128:129], off offset:512
	v_lshlrev_b64 v[128:129], 14, v[216:217]
	s_waitcnt vmcnt(12)
	v_pk_mul_f32 v[134:135], v[142:143], v[134:135]
	v_pk_mul_f32 v[132:133], v[140:141], v[132:133]
	v_pk_mul_f32 v[130:131], v[138:139], v[130:131]
	v_lshl_add_u64 v[136:137], v[212:213], 0, v[128:129]
	v_pk_mul_f32 v[206:207], v[134:135], s[24:25] op_sel_hi:[1,0]
	v_pk_mul_f32 v[208:209], v[132:133], s[24:25] op_sel_hi:[1,0]
	v_pk_mul_f32 v[204:205], v[130:131], s[24:25] op_sel_hi:[1,0]
	global_load_dwordx4 v[132:135], v[136:137], off offset:16
	global_load_dwordx4 v[140:143], v[136:137], off
	global_load_dwordx4 v[128:131], v[136:137], off offset:528
	s_nop 0
	global_load_dwordx4 v[136:139], v[136:137], off offset:512
	s_nop 0
	global_load_dword v222, v[210:211], off
	s_waitcnt vmcnt(0)
	v_pk_mul_f32 v[124:125], v[222:223], v[124:125] op_sel_hi:[0,1]
	v_pk_mul_f32 v[126:127], v[222:223], v[126:127] op_sel_hi:[0,1]
	v_pk_fma_f32 v[126:127], v[194:195], v[126:127], v[236:237]
	v_pk_fma_f32 v[124:125], v[196:197], v[124:125], v[234:235]
	v_pk_mul_f32 v[120:121], v[222:223], v[120:121] op_sel_hi:[0,1]
	v_pk_mul_f32 v[122:123], v[222:223], v[122:123] op_sel_hi:[0,1]
	v_pk_fma_f32 v[186:187], v[198:199], v[122:123], v[186:187]
	v_pk_fma_f32 v[122:123], v[200:201], v[120:121], v[184:185]
	v_mul_f32_e32 v120, v125, v125
	v_mul_f32_e32 v121, v127, v127
	v_fmac_f32_e32 v120, v124, v124
	v_fmac_f32_e32 v121, v126, v126
	v_add_f32_e32 v120, v120, v121
	v_mul_f32_e32 v121, v123, v123
	v_fmac_f32_e32 v121, v122, v122
	v_add_f32_e32 v120, v121, v120
	v_mul_f32_e32 v121, v187, v187
	v_fmac_f32_e32 v121, v186, v186
	v_add_f32_e32 v184, v121, v120
	v_cvt_pk_bf16_f32 v120, v124, v125
	v_lshl_add_u64 v[124:125], s[16:17], 0, v[238:239]
	v_pk_mul_f32 v[116:117], v[222:223], v[116:117] op_sel_hi:[0,1]
	v_pk_mul_f32 v[118:119], v[222:223], v[118:119] op_sel_hi:[0,1]
	v_cvt_pk_bf16_f32 v121, v126, v127
	v_cvt_pk_bf16_f32 v122, v122, v123
	v_cvt_pk_bf16_f32 v123, v186, v187
	v_lshl_add_u64 v[124:125], v[192:193], 1, v[124:125]
	v_pk_fma_f32 v[118:119], v[206:207], v[118:119], v[182:183]
	v_pk_fma_f32 v[116:117], v[208:209], v[116:117], v[180:181]
	v_pk_mul_f32 v[112:113], v[222:223], v[112:113] op_sel_hi:[0,1]
	v_pk_mul_f32 v[114:115], v[222:223], v[114:115] op_sel_hi:[0,1]
	global_store_dwordx4 v[124:125], v[120:123], off
	s_nop 1
	v_pk_fma_f32 v[120:121], v[204:205], v[114:115], v[178:179]
	v_pk_fma_f32 v[114:115], v[202:203], v[112:113], v[176:177]
	v_mul_f32_e32 v112, v117, v117
	v_mul_f32_e32 v113, v119, v119
	v_fmac_f32_e32 v112, v116, v116
	v_fmac_f32_e32 v113, v118, v118
	v_add_f32_e32 v112, v112, v113
	v_mul_f32_e32 v113, v115, v115
	v_fmac_f32_e32 v113, v114, v114
	v_add_f32_e32 v112, v113, v112
	v_mul_f32_e32 v113, v121, v121
	v_fmac_f32_e32 v113, v120, v120
	v_add_f32_e32 v112, v113, v112
	v_add_f32_e32 v122, v184, v112
	v_cvt_pk_bf16_f32 v112, v116, v117
	v_cvt_pk_bf16_f32 v113, v118, v119
	v_cvt_pk_bf16_f32 v114, v114, v115
	v_cvt_pk_bf16_f32 v115, v120, v121
	global_store_dwordx4 v[124:125], v[112:115], off offset:256
	ds_bpermute_b32 v112, v227, v122
	s_waitcnt lgkmcnt(0)
	v_add_f32_e32 v112, v122, v112
	ds_bpermute_b32 v113, v228, v112
	s_and_saveexec_b64 s[38:39], vcc
	s_cbranch_execz .LBB0_1498
	v_lshlrev_b64 v[114:115], 8, v[214:215]
	v_lshl_add_u64 v[114:115], s[10:11], 0, v[114:115]
	v_lshl_add_u64 v[114:115], s[36:37], 2, v[114:115]
	s_lshl_b32 s22, s50, 2
	v_lshl_add_u64 v[114:115], v[114:115], 0, s[22:23]
	s_waitcnt lgkmcnt(0)
	v_add_f32_e32 v112, v112, v113
	global_store_dword v[114:115], v112, off

.LBB0_1684:
	v_mov_b32_e32 v130, v223
	s_lshl_b32 s13, s20, 8
	s_lshl_b32 s15, s40, 8
	v_ashrrev_i32_e32 v128, 1, v130
	s_add_i32 s13, s13, s21
	s_or_b32 s15, s15, s38
	v_and_b32_e32 v128, -8, v128
	v_add_u32_e32 v128, s15, v128
	v_and_or_b32 v152, v130, 15, s13
	v_ashrrev_i32_e32 v129, 31, v128
	v_ashrrev_i32_e32 v153, 31, v152
	v_lshl_add_u64 v[150:151], v[128:129], 1, s[8:9]
	v_lshlrev_b64 v[130:131], 13, v[152:153]
	v_or_b32_e32 v184, 16, v152
	v_lshl_add_u64 v[130:131], v[150:151], 0, v[130:131]
	v_ashrrev_i32_e32 v185, 31, v184
	global_load_dwordx4 v[164:167], v[130:131], off
	global_load_dwordx4 v[168:171], v[130:131], off offset:256
	v_lshlrev_b64 v[130:131], 13, v[184:185]
	v_lshlrev_b64 v[148:149], 2, v[128:129]
	v_lshl_add_u64 v[130:131], v[150:151], 0, v[130:131]
	v_lshl_add_u64 v[128:129], s[6:7], 0, v[148:149]
	v_or_b32_e32 v196, 32, v152
	global_load_dwordx4 v[172:175], v[130:131], off
	global_load_dwordx4 v[176:179], v[130:131], off offset:256
	global_load_dwordx4 v[140:143], v[128:129], off
	global_load_dwordx4 v[136:139], v[128:129], off offset:16
	global_load_dwordx4 v[132:135], v[128:129], off offset:512
	s_nop 0
	global_load_dwordx4 v[128:131], v[128:129], off offset:528
	v_ashrrev_i32_e32 v197, 31, v196
	v_lshlrev_b64 v[154:155], 13, v[196:197]
	v_lshl_add_u64 v[186:187], v[150:151], 0, v[154:155]
	global_load_dwordx4 v[180:183], v[186:187], off
	v_or_b32_e32 v154, 48, v152
	v_ashrrev_i32_e32 v155, 31, v154
	v_lshlrev_b64 v[192:193], 14, v[184:185]
	global_load_dwordx4 v[184:187], v[186:187], off offset:256
	v_lshlrev_b64 v[188:189], 14, v[152:153]
	v_lshlrev_b64 v[190:191], 13, v[154:155]
	v_lshl_add_u64 v[188:189], s[4:5], 0, v[188:189]
	v_lshl_add_u64 v[192:193], s[4:5], 0, v[192:193]
	v_lshl_add_u64 v[194:195], v[150:151], 0, v[190:191]
	v_lshl_add_u64 v[198:199], v[188:189], 0, v[148:149]
	v_lshl_add_u64 v[200:201], v[192:193], 0, v[148:149]
	global_load_dwordx4 v[188:191], v[194:195], off
	s_nop 0
	global_load_dwordx4 v[192:195], v[194:195], off offset:256
	s_andn2_b64 vcc, exec, s[0:1]
	s_mov_b64 s[0:1], -1
	s_cmp_lg_u64 s[10:11], 0
	s_cbranch_scc0 .Lhs_p9
	s_barrier
.Lhs_p9:
	s_waitcnt vmcnt(11)
	v_lshlrev_b32_e32 v202, 16, v164
	v_and_b32_e32 v203, 0xffff0000, v164
	v_lshlrev_b32_e32 v164, 16, v165
	v_and_b32_e32 v165, 0xffff0000, v165
	s_waitcnt vmcnt(10)
	v_lshlrev_b32_e32 v206, 16, v168
	v_and_b32_e32 v207, 0xffff0000, v168
	v_lshlrev_b32_e32 v208, 16, v170
	v_and_b32_e32 v209, 0xffff0000, v170
	v_lshlrev_b32_e32 v170, 16, v171
	v_and_b32_e32 v171, 0xffff0000, v171
	v_lshlrev_b32_e32 v204, 16, v166
	v_and_b32_e32 v205, 0xffff0000, v166
	v_lshlrev_b32_e32 v166, 16, v167
	v_and_b32_e32 v167, 0xffff0000, v167
	v_lshlrev_b32_e32 v168, 16, v169
	v_and_b32_e32 v169, 0xffff0000, v169
	s_waitcnt vmcnt(9)
	v_lshlrev_b32_e32 v210, 16, v172
	v_and_b32_e32 v211, 0xffff0000, v172
	v_lshlrev_b32_e32 v172, 16, v173
	v_and_b32_e32 v173, 0xffff0000, v173
	v_lshlrev_b32_e32 v212, 16, v174
	v_and_b32_e32 v213, 0xffff0000, v174
	v_lshlrev_b32_e32 v174, 16, v175
	v_and_b32_e32 v175, 0xffff0000, v175
	s_waitcnt vmcnt(7)
	v_pk_fma_f32 v[126:127], v[126:127], v[142:143], v[164:165]
	v_pk_fma_f32 v[124:125], v[124:125], v[140:141], v[202:203]
	s_waitcnt vmcnt(5)
	v_pk_fma_f32 v[108:109], v[108:109], v[132:133], v[206:207]
	s_waitcnt vmcnt(4)
	v_pk_fma_f32 v[106:107], v[106:107], v[130:131], v[170:171]
	v_pk_fma_f32 v[122:123], v[122:123], v[138:139], v[166:167]
	v_pk_fma_f32 v[120:121], v[120:121], v[136:137], v[204:205]
	v_pk_fma_f32 v[110:111], v[110:111], v[134:135], v[168:169]
	v_pk_fma_f32 v[104:105], v[104:105], v[128:129], v[208:209]
	v_pk_fma_f32 v[118:119], v[118:119], v[142:143], v[172:173]
	v_pk_fma_f32 v[116:117], v[116:117], v[140:141], v[210:211]
	v_pk_fma_f32 v[114:115], v[114:115], v[138:139], v[174:175]
	v_pk_fma_f32 v[112:113], v[112:113], v[136:137], v[212:213]
	global_store_dwordx4 v[198:199], v[124:127], off
	global_store_dwordx4 v[198:199], v[120:123], off offset:16
	global_store_dwordx4 v[198:199], v[108:111], off offset:512
	global_store_dwordx4 v[198:199], v[104:107], off offset:528
	global_store_dwordx4 v[200:201], v[116:119], off
	global_store_dwordx4 v[200:201], v[112:115], off offset:16
	v_lshlrev_b32_e32 v106, 16, v178
	v_and_b32_e32 v107, 0xffff0000, v178
	v_lshlrev_b32_e32 v108, 16, v179
	v_and_b32_e32 v109, 0xffff0000, v179
	v_pk_fma_f32 v[94:95], v[94:95], v[130:131], v[108:109]
	v_pk_fma_f32 v[92:93], v[92:93], v[128:129], v[106:107]
	global_store_dwordx4 v[200:201], v[92:95], off offset:528
	v_lshlrev_b32_e32 v214, 16, v176
	v_and_b32_e32 v215, 0xffff0000, v176
	s_waitcnt vmcnt(10)
	v_lshlrev_b32_e32 v92, 16, v180
	v_and_b32_e32 v93, 0xffff0000, v180
	v_pk_fma_f32 v[92:93], v[96:97], v[140:141], v[92:93]
	v_lshlrev_b64 v[96:97], 14, v[196:197]
	v_lshlrev_b32_e32 v104, 16, v177
	v_and_b32_e32 v105, 0xffff0000, v177
	v_lshlrev_b32_e32 v94, 16, v181
	v_and_b32_e32 v95, 0xffff0000, v181
	v_lshl_add_u64 v[96:97], s[4:5], 0, v[96:97]
	v_pk_fma_f32 v[102:103], v[102:103], v[134:135], v[104:105]
	v_pk_fma_f32 v[100:101], v[100:101], v[132:133], v[214:215]
	v_pk_fma_f32 v[94:95], v[98:99], v[142:143], v[94:95]
	v_lshl_add_u64 v[96:97], v[96:97], 0, v[148:149]
	global_store_dwordx4 v[200:201], v[100:103], off offset:512
	global_store_dwordx4 v[96:97], v[92:95], off
	v_add_u32_e32 v98, 0x90, v152
	v_lshlrev_b32_e32 v100, 16, v182
	v_and_b32_e32 v101, 0xffff0000, v182
	v_lshlrev_b32_e32 v102, 16, v183
	v_and_b32_e32 v103, 0xffff0000, v183
	s_waitcnt vmcnt(11)
	v_lshlrev_b32_e32 v92, 16, v186
	v_and_b32_e32 v93, 0xffff0000, v186
	v_lshlrev_b32_e32 v94, 16, v187
	v_and_b32_e32 v95, 0xffff0000, v187
	v_pk_fma_f32 v[90:91], v[90:91], v[138:139], v[102:103]
	v_pk_fma_f32 v[88:89], v[88:89], v[136:137], v[100:101]
	v_pk_fma_f32 v[78:79], v[78:79], v[130:131], v[94:95]
	v_pk_fma_f32 v[76:77], v[76:77], v[128:129], v[92:93]
	global_store_dwordx4 v[96:97], v[88:91], off offset:16
	global_store_dwordx4 v[96:97], v[76:79], off offset:528
	v_ashrrev_i32_e32 v99, 31, v98
	v_lshlrev_b32_e32 v88, 16, v184
	v_and_b32_e32 v89, 0xffff0000, v184
	v_lshlrev_b32_e32 v90, 16, v185
	v_and_b32_e32 v91, 0xffff0000, v185
	s_waitcnt vmcnt(12)
	v_lshlrev_b32_e32 v76, 16, v188
	v_and_b32_e32 v77, 0xffff0000, v188
	v_pk_fma_f32 v[86:87], v[86:87], v[134:135], v[90:91]
	v_pk_fma_f32 v[84:85], v[84:85], v[132:133], v[88:89]
	v_pk_fma_f32 v[76:77], v[80:81], v[140:141], v[76:77]
	v_lshlrev_b64 v[80:81], 14, v[154:155]
	global_store_dwordx4 v[96:97], v[84:87], off offset:512
	v_lshlrev_b32_e32 v78, 16, v189
	v_and_b32_e32 v79, 0xffff0000, v189
	v_lshlrev_b32_e32 v84, 16, v190
	v_and_b32_e32 v85, 0xffff0000, v190
	v_lshlrev_b32_e32 v86, 16, v191
	v_and_b32_e32 v87, 0xffff0000, v191
	v_lshl_add_u64 v[80:81], s[4:5], 0, v[80:81]
	v_pk_fma_f32 v[78:79], v[82:83], v[142:143], v[78:79]
	v_lshl_add_u64 v[80:81], v[80:81], 0, v[148:149]
	v_pk_fma_f32 v[74:75], v[74:75], v[138:139], v[86:87]
	v_pk_fma_f32 v[72:73], v[72:73], v[136:137], v[84:85]
	global_store_dwordx4 v[80:81], v[76:79], off
	global_store_dwordx4 v[80:81], v[72:75], off offset:16
	v_add_u32_e32 v96, 0x80, v152
	s_waitcnt vmcnt(14)
	v_lshlrev_b32_e32 v76, 16, v194
	v_lshlrev_b32_e32 v72, 16, v192
	v_and_b32_e32 v73, 0xffff0000, v192
	v_lshlrev_b32_e32 v74, 16, v193
	v_and_b32_e32 v75, 0xffff0000, v193
	v_and_b32_e32 v77, 0xffff0000, v194
	v_lshlrev_b32_e32 v78, 16, v195
	v_and_b32_e32 v79, 0xffff0000, v195
	v_pk_fma_f32 v[70:71], v[70:71], v[134:135], v[74:75]
	v_pk_fma_f32 v[68:69], v[68:69], v[132:133], v[72:73]
	v_pk_fma_f32 v[66:67], v[66:67], v[130:131], v[78:79]
	v_pk_fma_f32 v[64:65], v[64:65], v[128:129], v[76:77]
	v_ashrrev_i32_e32 v97, 31, v96
	global_store_dwordx4 v[80:81], v[68:71], off offset:512
	global_store_dwordx4 v[80:81], v[64:67], off offset:528
	v_add_u32_e32 v100, 0xa0, v152
	v_ashrrev_i32_e32 v101, 31, v100
	v_lshlrev_b64 v[64:65], 13, v[96:97]
	v_lshl_add_u64 v[64:65], v[150:151], 0, v[64:65]
	global_load_dwordx4 v[68:71], v[64:65], off
	global_load_dwordx4 v[72:75], v[64:65], off offset:256
	v_lshlrev_b64 v[64:65], 13, v[98:99]
	v_lshl_add_u64 v[64:65], v[150:151], 0, v[64:65]
	global_load_dwordx4 v[76:79], v[64:65], off
	global_load_dwordx4 v[80:83], v[64:65], off offset:256
	v_lshlrev_b64 v[64:65], 13, v[100:101]
	v_lshl_add_u64 v[64:65], v[150:151], 0, v[64:65]
	global_load_dwordx4 v[84:87], v[64:65], off
	global_load_dwordx4 v[88:91], v[64:65], off offset:256
	v_add_u32_e32 v102, 0xb0, v152
	v_ashrrev_i32_e32 v103, 31, v102
	v_lshlrev_b64 v[64:65], 13, v[102:103]
	v_lshl_add_u64 v[64:65], v[150:151], 0, v[64:65]
	global_load_dwordx4 v[92:95], v[64:65], off
	s_nop 0
	global_load_dwordx4 v[64:67], v[64:65], off offset:256
	s_waitcnt vmcnt(7)
	v_lshlrev_b32_e32 v104, 16, v68
	v_and_b32_e32 v105, 0xffff0000, v68
	v_lshlrev_b32_e32 v68, 16, v69
	v_and_b32_e32 v69, 0xffff0000, v69
	v_pk_fma_f32 v[62:63], v[62:63], v[142:143], v[68:69]
	v_lshlrev_b64 v[68:69], 14, v[96:97]
	v_lshl_add_u64 v[68:69], s[4:5], 0, v[68:69]
	v_pk_fma_f32 v[60:61], v[60:61], v[140:141], v[104:105]
	v_lshl_add_u64 v[68:69], v[68:69], 0, v[148:149]
	global_store_dwordx4 v[68:69], v[60:63], off
	v_lshlrev_b32_e32 v106, 16, v70
	v_and_b32_e32 v107, 0xffff0000, v70
	s_waitcnt vmcnt(7)
	v_lshlrev_b32_e32 v60, 16, v74
	v_and_b32_e32 v61, 0xffff0000, v74
	v_lshlrev_b32_e32 v62, 16, v75
	v_and_b32_e32 v63, 0xffff0000, v75
	v_pk_fma_f32 v[46:47], v[46:47], v[130:131], v[62:63]
	v_pk_fma_f32 v[44:45], v[44:45], v[128:129], v[60:61]
	global_store_dwordx4 v[68:69], v[44:47], off offset:528
	v_lshlrev_b32_e32 v70, 16, v71
	v_and_b32_e32 v71, 0xffff0000, v71
	s_waitcnt vmcnt(7)
	v_lshlrev_b32_e32 v44, 16, v76
	v_and_b32_e32 v45, 0xffff0000, v76
	v_pk_fma_f32 v[44:45], v[48:49], v[140:141], v[44:45]
	v_lshlrev_b64 v[48:49], 14, v[98:99]
	v_lshlrev_b32_e32 v46, 16, v77
	v_and_b32_e32 v47, 0xffff0000, v77
	v_lshl_add_u64 v[48:49], s[4:5], 0, v[48:49]
	v_pk_fma_f32 v[58:59], v[58:59], v[138:139], v[70:71]
	v_pk_fma_f32 v[56:57], v[56:57], v[136:137], v[106:107]
	v_pk_fma_f32 v[46:47], v[50:51], v[142:143], v[46:47]
	v_lshl_add_u64 v[48:49], v[48:49], 0, v[148:149]
	global_store_dwordx4 v[68:69], v[56:59], off offset:16
	global_store_dwordx4 v[48:49], v[44:47], off
	s_nop 0
	v_lshlrev_b32_e32 v56, 16, v72
	v_and_b32_e32 v57, 0xffff0000, v72
	v_lshlrev_b32_e32 v58, 16, v73
	v_and_b32_e32 v59, 0xffff0000, v73
	s_waitcnt vmcnt(8)
	v_lshlrev_b32_e32 v44, 16, v82
	v_and_b32_e32 v45, 0xffff0000, v82
	v_lshlrev_b32_e32 v46, 16, v83
	v_and_b32_e32 v47, 0xffff0000, v83
	v_pk_fma_f32 v[54:55], v[54:55], v[134:135], v[58:59]
	v_pk_fma_f32 v[52:53], v[52:53], v[132:133], v[56:57]
	v_pk_fma_f32 v[30:31], v[30:31], v[130:131], v[46:47]
	v_pk_fma_f32 v[28:29], v[28:29], v[128:129], v[44:45]
	global_store_dwordx4 v[68:69], v[52:55], off offset:512
	global_store_dwordx4 v[48:49], v[28:31], off offset:528
	s_nop 0
	v_lshlrev_b32_e32 v52, 16, v78
	v_and_b32_e32 v53, 0xffff0000, v78
	v_lshlrev_b32_e32 v54, 16, v79
	v_and_b32_e32 v55, 0xffff0000, v79
	s_waitcnt vmcnt(9)
	v_lshlrev_b32_e32 v28, 16, v84
	v_and_b32_e32 v29, 0xffff0000, v84
	v_pk_fma_f32 v[42:43], v[42:43], v[138:139], v[54:55]
	v_pk_fma_f32 v[40:41], v[40:41], v[136:137], v[52:53]
	v_pk_fma_f32 v[28:29], v[32:33], v[140:141], v[28:29]
	v_lshlrev_b64 v[32:33], 14, v[100:101]
	global_store_dwordx4 v[48:49], v[40:43], off offset:16
	v_lshlrev_b32_e32 v30, 16, v85
	v_and_b32_e32 v31, 0xffff0000, v85
	v_lshlrev_b32_e32 v40, 16, v80
	v_and_b32_e32 v41, 0xffff0000, v80
	v_lshlrev_b32_e32 v42, 16, v81
	v_and_b32_e32 v43, 0xffff0000, v81
	v_lshl_add_u64 v[32:33], s[4:5], 0, v[32:33]
	v_pk_fma_f32 v[38:39], v[38:39], v[134:135], v[42:43]
	v_pk_fma_f32 v[36:37], v[36:37], v[132:133], v[40:41]
	v_pk_fma_f32 v[30:31], v[34:35], v[142:143], v[30:31]
	v_lshl_add_u64 v[32:33], v[32:33], 0, v[148:149]
	global_store_dwordx4 v[48:49], v[36:39], off offset:512
	global_store_dwordx4 v[32:33], v[28:31], off
	s_nop 0
	v_lshlrev_b32_e32 v36, 16, v86
	v_and_b32_e32 v37, 0xffff0000, v86
	v_lshlrev_b32_e32 v38, 16, v87
	v_and_b32_e32 v39, 0xffff0000, v87
	s_waitcnt vmcnt(11)
	v_lshlrev_b32_e32 v28, 16, v90
	v_and_b32_e32 v29, 0xffff0000, v90
	v_lshlrev_b32_e32 v30, 16, v91
	v_and_b32_e32 v31, 0xffff0000, v91
	v_pk_fma_f32 v[26:27], v[26:27], v[138:139], v[38:39]
	v_pk_fma_f32 v[24:25], v[24:25], v[136:137], v[36:37]
	v_pk_fma_f32 v[14:15], v[14:15], v[130:131], v[30:31]
	v_pk_fma_f32 v[12:13], v[12:13], v[128:129], v[28:29]
	global_store_dwordx4 v[32:33], v[24:27], off offset:16
	global_store_dwordx4 v[32:33], v[12:15], off offset:528
	s_nop 0
	v_lshlrev_b32_e32 v24, 16, v88
	v_and_b32_e32 v25, 0xffff0000, v88
	v_lshlrev_b32_e32 v26, 16, v89
	v_and_b32_e32 v27, 0xffff0000, v89
	s_waitcnt vmcnt(12)
	v_lshlrev_b32_e32 v12, 16, v92
	v_and_b32_e32 v13, 0xffff0000, v92
	v_pk_fma_f32 v[22:23], v[22:23], v[134:135], v[26:27]
	v_pk_fma_f32 v[20:21], v[20:21], v[132:133], v[24:25]
	v_pk_fma_f32 v[12:13], v[16:17], v[140:141], v[12:13]
	v_lshlrev_b64 v[16:17], 14, v[102:103]
	global_store_dwordx4 v[32:33], v[20:23], off offset:512
	v_lshlrev_b32_e32 v14, 16, v93
	v_and_b32_e32 v15, 0xffff0000, v93
	v_lshlrev_b32_e32 v20, 16, v94
	v_and_b32_e32 v21, 0xffff0000, v94
	v_lshlrev_b32_e32 v22, 16, v95
	v_and_b32_e32 v23, 0xffff0000, v95
	v_lshl_add_u64 v[16:17], s[4:5], 0, v[16:17]
	v_pk_fma_f32 v[14:15], v[18:19], v[142:143], v[14:15]
	v_lshl_add_u64 v[16:17], v[16:17], 0, v[148:149]
	v_pk_fma_f32 v[10:11], v[10:11], v[138:139], v[22:23]
	v_pk_fma_f32 v[8:9], v[8:9], v[136:137], v[20:21]
	global_store_dwordx4 v[16:17], v[12:15], off
	global_store_dwordx4 v[16:17], v[8:11], off offset:16
	s_waitcnt vmcnt(14)
	v_lshlrev_b32_e32 v12, 16, v66
	v_lshlrev_b32_e32 v8, 16, v64
	v_and_b32_e32 v9, 0xffff0000, v64
	v_lshlrev_b32_e32 v10, 16, v65
	v_and_b32_e32 v11, 0xffff0000, v65
	v_and_b32_e32 v13, 0xffff0000, v66
	v_lshlrev_b32_e32 v14, 16, v67
	v_and_b32_e32 v15, 0xffff0000, v67
	v_pk_fma_f32 v[6:7], v[6:7], v[134:135], v[10:11]
	v_pk_fma_f32 v[4:5], v[4:5], v[132:133], v[8:9]
	v_pk_fma_f32 v[2:3], v[2:3], v[130:131], v[14:15]
	v_pk_fma_f32 v[0:1], v[0:1], v[128:129], v[12:13]
	global_store_dwordx4 v[16:17], v[4:7], off offset:512
	global_store_dwordx4 v[16:17], v[0:3], off offset:528
	s_cbranch_vccnz .LBB0_1673
	s_andn2_b64 vcc, exec, s[2:3]
	s_cbranch_vccnz .LBB0_1672
	s_mov_b32 s99, 1
	s_branch .LBB0_1672
